# rows phase: runs of serialized dt-weight LDS reads batched into spare quads with counted lgkmcnt waits (37 of 96 groups)
# baseline (speedup 1.0000x reference)
.LBB0_464:
	v_readlane_b32 s2, v254, 27
	v_readlane_b32 s3, v254, 28
	s_andn2_b64 vcc, exec, s[2:3]
	s_nop 0
	v_cndmask_b32_e64 v84, 0, 1, s[2:3]
	v_cmp_ne_u32_e64 s[48:49], 1, v84
	s_cbranch_vccnz .LBB0_468
	s_waitcnt vmcnt(10)
	v_mov_b32_e32 v86, v5
	v_mov_b32_e32 v87, v1
	v_mov_b32_e32 v84, v4
	v_mov_b32_e32 v85, v0
	v_pk_mul_f32 v[86:87], v[86:87], v[86:87]
	s_waitcnt vmcnt(8)
	v_mov_b32_e32 v88, v15
	v_pk_fma_f32 v[84:85], v[84:85], v[84:85], v[86:87]
	v_mov_b32_e32 v86, v6
	v_mov_b32_e32 v87, v2
	v_pk_fma_f32 v[84:85], v[86:87], v[86:87], v[84:85]
	v_mov_b32_e32 v86, v7
	v_mov_b32_e32 v87, v3
	v_mov_b32_e32 v89, v11
	v_pk_fma_f32 v[84:85], v[86:87], v[86:87], v[84:85]
	v_mov_b32_e32 v86, v14
	v_mov_b32_e32 v87, v10
	v_pk_mul_f32 v[88:89], v[88:89], v[88:89]
	v_add_f32_e32 v84, v84, v85
	v_pk_fma_f32 v[86:87], v[86:87], v[86:87], v[88:89]
	v_mov_b32_e32 v88, v16
	v_mov_b32_e32 v89, v12
	v_pk_fma_f32 v[86:87], v[88:89], v[88:89], v[86:87]
	v_mov_b32_e32 v88, v17
	v_mov_b32_e32 v89, v13
	v_pk_fma_f32 v[86:87], v[88:89], v[88:89], v[86:87]
	v_add_f32_e32 v84, v87, v84
	v_add_f32_e32 v84, v86, v84
	s_mov_b32 s2, 0x800000
	s_and_b32 s1, s1, 0xfffff000
	ds_bpermute_b32 v86, v249, v84
	v_add_u32_e32 v98, s1, v101
	ds_read_b128 v[104:107], v98
	v_readlane_b32 s60, v251, 10
	v_readlane_b32 s62, v251, 12
	s_waitcnt lgkmcnt(1)
	v_add_f32_e32 v84, v84, v86
	v_readlane_b32 s63, v251, 13
	v_readlane_b32 s61, v251, 11
	ds_bpermute_b32 v86, v248, v84
	s_waitcnt lgkmcnt(0)
	v_add_f32_e32 v84, v84, v86
	s_nop 1
	ds_bpermute_b32 v86, v247, v84
	s_waitcnt lgkmcnt(0)
	v_add_f32_e32 v84, v84, v86
	s_nop 1
	ds_bpermute_b32 v86, v246, v84
	s_waitcnt lgkmcnt(0)
	v_add_f32_e32 v84, v84, v86
	s_nop 1
	ds_bpermute_b32 v86, v245, v84
	s_waitcnt lgkmcnt(0)
	v_add_f32_e32 v84, v84, v86
	s_nop 1
	ds_bpermute_b32 v85, v244, v84
	ds_read_b128 v[86:89], v100 offset:36864
	s_waitcnt lgkmcnt(1)
	v_add_f32_e32 v84, v84, v85
	v_fmamk_f32 v84, v84, 0x3a800000, v218
	v_cmp_gt_f32_e32 vcc, s2, v84
	v_mul_f32_e32 v85, 0x4b800000, v84
	s_nop 0
	v_cndmask_b32_e32 v84, v84, v85, vcc
	v_rsq_f32_e32 v84, v84
	s_nop 0
	v_mul_f32_e32 v85, 0x45800000, v84
	v_cndmask_b32_e32 v84, v84, v85, vcc
	v_add_u32_e32 v85, s1, v102
	ds_read_b128 v[108:111], v85
	v_pk_mul_f32 v[90:91], v[0:1], v[84:85] op_sel_hi:[1,0]
	s_mov_b32 s1, 0xb00000
	s_waitcnt lgkmcnt(1)
	v_pk_mul_f32 v[86:87], v[86:87], v[90:91]
	v_pk_add_f32 v[90:91], v[104:105], 1.0 op_sel_hi:[1,0]
	v_pk_mul_f32 v[118:119], v[4:5], v[84:85] op_sel_hi:[1,0]
	s_waitcnt lgkmcnt(0)
	v_pk_fma_f32 v[112:113], v[90:91], v[86:87], v[108:109]
	v_pk_mul_f32 v[86:87], v[2:3], v[84:85] op_sel_hi:[1,0]
	s_nop 0
	v_pk_mul_f32 v[86:87], v[88:89], v[86:87]
	v_pk_add_f32 v[88:89], v[106:107], 1.0 op_sel_hi:[1,0]
	s_nop 0
	v_pk_fma_f32 v[110:111], v[88:89], v[86:87], v[110:111]
	v_lshl_add_u64 v[86:87], s[62:63], 0, v[70:71]
	v_add_co_u32_e32 v86, vcc, s1, v86
	v_cvt_pk_bf16_f32 v88, v112, v113
	v_cvt_pk_bf16_f32 v89, v110, v111
	v_addc_co_u32_e32 v87, vcc, 0, v87, vcc
	global_store_dwordx2 v[86:87], v[88:89], off
	ds_read_b128 v[172:175], v100
	ds_read_b128 v[176:179], v100 offset:4096
	ds_read_b128 v[180:183], v100 offset:8192
	ds_read_b128 v[184:187], v100 offset:12288
	ds_read_b128 v[188:191], v100 offset:16384
	ds_read_b128 v[204:207], v100 offset:20480
	ds_read_b128 v[208:211], v100 offset:24576
	ds_read_b128 v[212:215], v100 offset:28672
	s_waitcnt lgkmcnt(7)
	v_mul_f32_e32 v173, v173, v113
	v_fmac_f32_e32 v173, v172, v112
	v_fmac_f32_e32 v173, v174, v110
	v_fmac_f32_e32 v173, v175, v111
	v_add_f32_e32 v107, 0, v173
	s_waitcnt lgkmcnt(6)
	v_mul_f32_e32 v177, v177, v113
	v_fmac_f32_e32 v177, v176, v112
	v_fmac_f32_e32 v177, v178, v110
	v_fmac_f32_e32 v177, v179, v111
	v_add_f32_e32 v109, 0, v177
	s_waitcnt lgkmcnt(5)
	v_mul_f32_e32 v181, v181, v113
	v_fmac_f32_e32 v181, v180, v112
	v_fmac_f32_e32 v181, v182, v110
	v_fmac_f32_e32 v181, v183, v111
	v_add_f32_e32 v108, 0, v181
	s_waitcnt lgkmcnt(4)
	v_mul_f32_e32 v185, v185, v113
	v_fmac_f32_e32 v185, v184, v112
	v_fmac_f32_e32 v185, v186, v110
	v_fmac_f32_e32 v185, v187, v111
	v_add_f32_e32 v106, 0, v185
	s_waitcnt lgkmcnt(3)
	v_mul_f32_e32 v189, v189, v113
	v_fmac_f32_e32 v189, v188, v112
	v_fmac_f32_e32 v189, v190, v110
	v_fmac_f32_e32 v189, v191, v111
	v_add_f32_e32 v105, 0, v189
	s_waitcnt lgkmcnt(2)
	v_mul_f32_e32 v205, v205, v113
	v_fmac_f32_e32 v205, v204, v112
	v_fmac_f32_e32 v205, v206, v110
	v_fmac_f32_e32 v205, v207, v111
	v_add_f32_e32 v104, 0, v205
	s_waitcnt lgkmcnt(1)
	v_mul_f32_e32 v209, v209, v113
	v_fmac_f32_e32 v209, v208, v112
	v_fmac_f32_e32 v209, v210, v110
	v_fmac_f32_e32 v209, v211, v111
	v_add_f32_e32 v103, 0, v209
	s_waitcnt lgkmcnt(0)
	v_mul_f32_e32 v213, v113, v213
	v_fmac_f32_e32 v213, v112, v212
	v_fmac_f32_e32 v213, v110, v214
	v_fmac_f32_e32 v213, v111, v215
	v_add_f32_e32 v99, 0, v213
	ds_read_b128 v[88:91], v100 offset:37888
	ds_read_b128 v[110:113], v98 offset:1024
	ds_read_b128 v[114:117], v85 offset:1024
	s_waitcnt lgkmcnt(2)
	v_pk_mul_f32 v[88:89], v[118:119], v[88:89]
	s_waitcnt lgkmcnt(1)
	v_pk_add_f32 v[110:111], v[110:111], 1.0 op_sel_hi:[1,0]
	s_waitcnt lgkmcnt(0)
	v_pk_fma_f32 v[88:89], v[88:89], v[110:111], v[114:115]
	v_pk_mul_f32 v[110:111], v[6:7], v[84:85] op_sel_hi:[1,0]
	s_nop 0
	v_pk_mul_f32 v[90:91], v[110:111], v[90:91]
	v_pk_add_f32 v[110:111], v[112:113], 1.0 op_sel_hi:[1,0]
	s_nop 0
	v_pk_fma_f32 v[90:91], v[90:91], v[110:111], v[116:117]
	v_cvt_pk_bf16_f32 v110, v88, v89
	v_cvt_pk_bf16_f32 v111, v90, v91
	global_store_dwordx2 v[86:87], v[110:111], off offset:512
	ds_read_b128 v[172:175], v100 offset:1024
	ds_read_b128 v[176:179], v100 offset:5120
	ds_read_b128 v[180:183], v100 offset:9216
	ds_read_b128 v[184:187], v100 offset:13312
	ds_read_b128 v[188:191], v100 offset:17408
	s_waitcnt lgkmcnt(4)
	v_mul_f32_e32 v173, v89, v173
	v_fmac_f32_e32 v173, v88, v172
	v_fmac_f32_e32 v173, v90, v174
	v_fmac_f32_e32 v173, v91, v175
	v_add_f32_e32 v107, v107, v173
	s_waitcnt lgkmcnt(3)
	v_mul_f32_e32 v177, v89, v177
	v_fmac_f32_e32 v177, v88, v176
	v_fmac_f32_e32 v177, v90, v178
	v_fmac_f32_e32 v177, v91, v179
	v_add_f32_e32 v116, v109, v177
	s_waitcnt lgkmcnt(2)
	v_mul_f32_e32 v109, v89, v181
	v_fmac_f32_e32 v109, v88, v180
	v_fmac_f32_e32 v109, v90, v182
	v_fmac_f32_e32 v109, v91, v183
	v_add_f32_e32 v117, v108, v109
	s_waitcnt lgkmcnt(1)
	v_mul_f32_e32 v185, v89, v185
	v_fmac_f32_e32 v185, v88, v184
	v_fmac_f32_e32 v185, v90, v186
	v_fmac_f32_e32 v185, v91, v187
	v_add_f32_e32 v106, v106, v185
	s_waitcnt lgkmcnt(0)
	v_mul_f32_e32 v189, v89, v189
	v_fmac_f32_e32 v189, v88, v188
	v_fmac_f32_e32 v189, v90, v190
	v_fmac_f32_e32 v189, v91, v191
	v_add_f32_e32 v118, v105, v189
	ds_read_b128 v[108:111], v100 offset:21504
	s_waitcnt lgkmcnt(0)
	v_mul_f32_e32 v105, v89, v109
	v_fmac_f32_e32 v105, v88, v108
	v_fmac_f32_e32 v105, v90, v110
	v_fmac_f32_e32 v105, v91, v111
	ds_read_b128 v[108:111], v100 offset:25600
	v_add_f32_e32 v119, v104, v105
	s_waitcnt lgkmcnt(0)
	v_mul_f32_e32 v104, v89, v109
	v_fmac_f32_e32 v104, v88, v108
	v_fmac_f32_e32 v104, v90, v110
	v_fmac_f32_e32 v104, v91, v111
	ds_read_b128 v[108:111], v100 offset:29696
	v_add_f32_e32 v120, v103, v104
	v_pk_mul_f32 v[104:105], v[10:11], v[84:85] op_sel_hi:[1,0]
	s_waitcnt lgkmcnt(0)
	v_mul_f32_e32 v89, v89, v109
	v_fmac_f32_e32 v89, v88, v108
	v_fmac_f32_e32 v89, v90, v110
	v_fmac_f32_e32 v89, v91, v111
	v_add_f32_e32 v121, v99, v89
	ds_read_b128 v[88:91], v100 offset:38912
	ds_read_b128 v[108:111], v98 offset:2048
	ds_read_b128 v[112:115], v85 offset:2048
	s_waitcnt lgkmcnt(2)
	v_pk_mul_f32 v[88:89], v[104:105], v[88:89]
	s_waitcnt lgkmcnt(1)
	v_pk_add_f32 v[104:105], v[108:109], 1.0 op_sel_hi:[1,0]
	s_waitcnt lgkmcnt(0)
	v_pk_fma_f32 v[112:113], v[88:89], v[104:105], v[112:113]
	v_pk_mul_f32 v[88:89], v[12:13], v[84:85] op_sel_hi:[1,0]
	s_nop 0
	v_pk_mul_f32 v[88:89], v[88:89], v[90:91]
	v_pk_add_f32 v[90:91], v[110:111], 1.0 op_sel_hi:[1,0]
	s_nop 0
	v_pk_fma_f32 v[110:111], v[88:89], v[90:91], v[114:115]
	v_cvt_pk_bf16_f32 v88, v112, v113
	v_cvt_pk_bf16_f32 v89, v110, v111
	global_store_dwordx2 v[86:87], v[88:89], off offset:1024
	ds_read_b128 v[172:175], v100 offset:2048
	ds_read_b128 v[176:179], v100 offset:6144
	ds_read_b128 v[180:183], v100 offset:10240
	ds_read_b128 v[184:187], v100 offset:14336
	s_waitcnt lgkmcnt(3)
	v_mul_f32_e32 v173, v113, v173
	v_fmac_f32_e32 v173, v112, v172
	v_fmac_f32_e32 v173, v110, v174
	v_fmac_f32_e32 v173, v111, v175
	v_add_f32_e32 v105, v107, v173
	s_waitcnt lgkmcnt(2)
	v_mul_f32_e32 v177, v113, v177
	v_fmac_f32_e32 v177, v112, v176
	v_fmac_f32_e32 v177, v110, v178
	v_fmac_f32_e32 v177, v111, v179
	v_add_f32_e32 v122, v116, v177
	s_waitcnt lgkmcnt(1)
	v_mul_f32_e32 v181, v113, v181
	v_fmac_f32_e32 v181, v112, v180
	v_fmac_f32_e32 v181, v110, v182
	v_fmac_f32_e32 v181, v111, v183
	v_add_f32_e32 v123, v117, v181
	s_waitcnt lgkmcnt(0)
	v_mul_f32_e32 v185, v113, v185
	v_fmac_f32_e32 v185, v112, v184
	v_fmac_f32_e32 v185, v110, v186
	v_fmac_f32_e32 v185, v111, v187
	v_add_f32_e32 v104, v106, v185
	ds_read_b128 v[88:91], v100 offset:18432
	ds_read_b128 v[106:109], v100 offset:30720
	s_waitcnt lgkmcnt(1)
	v_mul_f32_e32 v89, v113, v89
	v_fmac_f32_e32 v89, v112, v88
	v_fmac_f32_e32 v89, v110, v90
	v_fmac_f32_e32 v89, v111, v91
	v_add_f32_e32 v103, v118, v89
	ds_read_b128 v[88:91], v100 offset:22528
	s_waitcnt lgkmcnt(0)
	v_mul_f32_e32 v89, v113, v89
	v_fmac_f32_e32 v89, v112, v88
	v_fmac_f32_e32 v89, v110, v90
	v_fmac_f32_e32 v89, v111, v91
	v_add_f32_e32 v99, v119, v89
	ds_read_b128 v[88:91], v100 offset:26624
	s_waitcnt lgkmcnt(0)
	v_mul_f32_e32 v89, v113, v89
	v_fmac_f32_e32 v89, v112, v88
	v_mul_f32_e32 v88, v113, v107
	v_fmac_f32_e32 v88, v112, v106
	v_fmac_f32_e32 v89, v110, v90
	v_fmac_f32_e32 v88, v110, v108
	v_fmac_f32_e32 v89, v111, v91
	v_fmac_f32_e32 v88, v111, v109
	ds_read_b128 v[106:109], v100 offset:39936
	ds_read_b128 v[110:113], v98 offset:3072
	ds_read_b128 v[114:117], v85 offset:3072
	v_add_f32_e32 v91, v120, v89
	v_add_f32_e32 v90, v121, v88
	v_pk_mul_f32 v[88:89], v[14:15], v[84:85] op_sel_hi:[1,0]
	v_pk_mul_f32 v[84:85], v[16:17], v[84:85] op_sel_hi:[1,0]
	s_waitcnt lgkmcnt(2)
	v_pk_mul_f32 v[88:89], v[88:89], v[106:107]
	s_waitcnt lgkmcnt(1)
	v_pk_add_f32 v[106:107], v[110:111], 1.0 op_sel_hi:[1,0]
	v_pk_mul_f32 v[84:85], v[84:85], v[108:109]
	s_waitcnt lgkmcnt(0)
	v_pk_fma_f32 v[88:89], v[88:89], v[106:107], v[114:115]
	v_pk_add_f32 v[106:107], v[112:113], 1.0 op_sel_hi:[1,0]
	s_nop 0
	v_pk_fma_f32 v[84:85], v[84:85], v[106:107], v[116:117]
	v_cvt_pk_bf16_f32 v106, v88, v89
	v_cvt_pk_bf16_f32 v107, v84, v85
	global_store_dwordx2 v[86:87], v[106:107], off offset:1536
	ds_read_b128 v[106:109], v100 offset:3072
	s_waitcnt lgkmcnt(0)
	v_mul_f32_e32 v86, v89, v107
	v_fmac_f32_e32 v86, v88, v106
	v_fmac_f32_e32 v86, v84, v108
	v_fmac_f32_e32 v86, v85, v109
	ds_read_b128 v[106:109], v100 offset:7168
	v_add_f32_e32 v86, v105, v86
	s_waitcnt lgkmcnt(0)
	v_mul_f32_e32 v87, v89, v107
	v_fmac_f32_e32 v87, v88, v106
	v_fmac_f32_e32 v87, v84, v108
	v_fmac_f32_e32 v87, v85, v109
	ds_read_b128 v[106:109], v100 offset:11264
	v_add_f32_e32 v87, v122, v87
	s_waitcnt lgkmcnt(0)
	v_mul_f32_e32 v98, v89, v107
	v_fmac_f32_e32 v98, v88, v106
	v_fmac_f32_e32 v98, v84, v108
	v_fmac_f32_e32 v98, v85, v109
	ds_read_b128 v[106:109], v100 offset:15360
	v_add_f32_e32 v98, v123, v98
	s_waitcnt lgkmcnt(0)
	v_mul_f32_e32 v105, v89, v107
	v_fmac_f32_e32 v105, v88, v106
	v_fmac_f32_e32 v105, v84, v108
	v_fmac_f32_e32 v105, v85, v109
	v_add_f32_e32 v108, v104, v105
	ds_read_b128 v[172:175], v100 offset:19456
	ds_read_b128 v[176:179], v100 offset:23552
	ds_read_b128 v[180:183], v100 offset:27648
	s_waitcnt lgkmcnt(2)
	v_mul_f32_e32 v173, v89, v173
	v_fmac_f32_e32 v173, v88, v172
	v_fmac_f32_e32 v173, v84, v174
	v_fmac_f32_e32 v173, v85, v175
	v_add_f32_e32 v103, v103, v173
	s_waitcnt lgkmcnt(1)
	v_mul_f32_e32 v177, v89, v177
	v_fmac_f32_e32 v177, v88, v176
	v_fmac_f32_e32 v177, v84, v178
	v_fmac_f32_e32 v177, v85, v179
	v_add_f32_e32 v99, v99, v177
	s_waitcnt lgkmcnt(0)
	v_mul_f32_e32 v181, v89, v181
	v_fmac_f32_e32 v181, v88, v180
	v_fmac_f32_e32 v181, v84, v182
	v_fmac_f32_e32 v181, v85, v183
	v_add_f32_e32 v91, v91, v181
	ds_read_b128 v[104:107], v100 offset:31744
	s_waitcnt lgkmcnt(0)
	v_mul_f32_e32 v89, v89, v105
	v_fmac_f32_e32 v89, v88, v104
	v_fmac_f32_e32 v89, v84, v106
	v_fmac_f32_e32 v89, v85, v107
	v_cndmask_b32_e64 v85, v103, v86, s[40:41]
	v_cndmask_b32_e64 v86, v86, v103, s[40:41]
	ds_bpermute_b32 v86, v249, v86
	v_cndmask_b32_e64 v88, v98, v91, s[40:41]
	ds_bpermute_b32 v88, v249, v88
	v_add_f32_e32 v84, v90, v89
	s_waitcnt lgkmcnt(1)
	v_add_f32_e32 v85, v85, v86
	v_cndmask_b32_e64 v86, v99, v87, s[40:41]
	v_cndmask_b32_e64 v87, v87, v99, s[40:41]
	ds_bpermute_b32 v87, v249, v87
	s_waitcnt lgkmcnt(0)
	v_add_f32_e32 v86, v86, v87
	v_cndmask_b32_e64 v87, v91, v98, s[40:41]
	v_add_f32_e32 v87, v87, v88
	v_cndmask_b32_e64 v88, v84, v108, s[40:41]
	v_cndmask_b32_e64 v84, v108, v84, s[40:41]
	ds_bpermute_b32 v84, v249, v84
	s_waitcnt lgkmcnt(0)
	v_add_f32_e32 v84, v88, v84
	v_cndmask_b32_e64 v88, v87, v85, s[42:43]
	v_cndmask_b32_e64 v85, v85, v87, s[42:43]
	v_cndmask_b32_e64 v87, v84, v86, s[42:43]
	v_cndmask_b32_e64 v84, v86, v84, s[42:43]
	ds_bpermute_b32 v85, v248, v85
	ds_bpermute_b32 v84, v248, v84
	s_waitcnt lgkmcnt(1)
	v_add_f32_e32 v85, v88, v85
	s_waitcnt lgkmcnt(0)
	v_add_f32_e32 v84, v87, v84
	v_cndmask_b32_e64 v86, v84, v85, s[44:45]
	v_cndmask_b32_e64 v84, v85, v84, s[44:45]
	ds_bpermute_b32 v84, v247, v84
	s_waitcnt lgkmcnt(0)
	v_add_f32_e32 v84, v86, v84
	ds_bpermute_b32 v85, v246, v84
	s_waitcnt lgkmcnt(0)
	v_add_f32_e32 v84, v84, v85
	ds_bpermute_b32 v85, v245, v84
	s_waitcnt lgkmcnt(0)
	v_add_f32_e32 v84, v84, v85
	ds_bpermute_b32 v85, v244, v84
	s_and_saveexec_b64 s[18:19], s[46:47]
	s_cbranch_execz .LBB0_467
	v_readlane_b32 s60, v251, 10
	v_readlane_b32 s62, v251, 12
	v_readlane_b32 s63, v251, 13
	s_waitcnt lgkmcnt(0)
	v_add_f32_e32 v86, v84, v85
	v_readlane_b32 s61, v251, 11
	v_lshl_add_u64 v[84:85], s[62:63], 0, v[68:69]
	global_store_dword v[84:85], v86, off

.LBB0_505:
	s_waitcnt vmcnt(6)
	v_mov_b32_e32 v78, v43
	v_mov_b32_e32 v79, v47
	v_mov_b32_e32 v76, v42
	v_mov_b32_e32 v77, v46
	v_pk_mul_f32 v[78:79], v[78:79], v[78:79]
	s_waitcnt vmcnt(4)
	v_mov_b32_e32 v80, v35
	v_pk_fma_f32 v[76:77], v[76:77], v[76:77], v[78:79]
	v_mov_b32_e32 v78, v44
	v_mov_b32_e32 v79, v48
	v_pk_fma_f32 v[76:77], v[78:79], v[78:79], v[76:77]
	v_mov_b32_e32 v78, v45
	v_mov_b32_e32 v79, v49
	v_mov_b32_e32 v81, v39
	v_pk_fma_f32 v[76:77], v[78:79], v[78:79], v[76:77]
	v_mov_b32_e32 v78, v34
	v_mov_b32_e32 v79, v38
	v_pk_mul_f32 v[80:81], v[80:81], v[80:81]
	v_add_f32_e32 v76, v76, v77
	v_pk_fma_f32 v[78:79], v[78:79], v[78:79], v[80:81]
	v_mov_b32_e32 v80, v36
	v_mov_b32_e32 v81, v40
	v_pk_fma_f32 v[78:79], v[80:81], v[80:81], v[78:79]
	v_mov_b32_e32 v80, v37
	v_mov_b32_e32 v81, v41
	v_pk_fma_f32 v[78:79], v[80:81], v[80:81], v[78:79]
	v_and_b32_e32 v77, 64, v220
	v_add_f32_e32 v76, v79, v76
	v_add_f32_e32 v76, v78, v76
	v_add_u32_e32 v77, 64, v77
	s_mov_b32 s2, 0x800000
	s_and_b32 s1, s1, 0xfffff000
	ds_bpermute_b32 v78, v249, v76
	v_add_u32_e32 v84, s1, v101
	ds_read_b128 v[86:89], v100 offset:36864
	ds_read_b128 v[90:93], v84
	s_ashr_i32 s53, s52, 31
	s_waitcnt lgkmcnt(2)
	v_add_f32_e32 v76, v76, v78
	s_nop 1
	ds_bpermute_b32 v78, v248, v76
	s_waitcnt lgkmcnt(0)
	v_add_f32_e32 v76, v76, v78
	s_nop 1
	ds_bpermute_b32 v78, v247, v76
	s_waitcnt lgkmcnt(0)
	v_add_f32_e32 v76, v76, v78
	s_nop 1
	ds_bpermute_b32 v78, v246, v76
	s_waitcnt lgkmcnt(0)
	v_add_f32_e32 v76, v76, v78
	s_nop 1
	ds_bpermute_b32 v83, v245, v76
	s_waitcnt lgkmcnt(0)
	v_add_f32_e32 v76, v76, v83
	v_xor_b32_e32 v83, 1, v220
	v_cmp_lt_i32_e32 vcc, v83, v77
	s_nop 1
	v_cndmask_b32_e32 v77, v220, v83, vcc
	v_lshlrev_b32_e32 v77, 2, v77
	ds_bpermute_b32 v83, v244, v76
	s_waitcnt lgkmcnt(0)
	v_add_f32_e32 v76, v76, v83
	v_fmamk_f32 v76, v76, 0x3a800000, v218
	v_cmp_gt_f32_e32 vcc, s2, v76
	v_mul_f32_e32 v83, 0x4b800000, v76
	s_lshl_b64 s[2:3], s[52:53], 11
	v_cndmask_b32_e32 v76, v76, v83, vcc
	v_rsq_f32_e32 v76, v76
	s_nop 0
	v_mul_f32_e32 v83, 0x45800000, v76
	v_cndmask_b32_e32 v76, v76, v83, vcc
	v_add_u32_e32 v83, s1, v102
	ds_read_b128 v[94:97], v83
	v_pk_mul_f32 v[46:47], v[46:47], v[76:77] op_sel_hi:[1,0]
	v_pk_mul_f32 v[42:43], v[42:43], v[76:77] op_sel_hi:[1,0]
	v_pk_mul_f32 v[46:47], v[86:87], v[46:47]
	v_pk_add_f32 v[86:87], v[90:91], 1.0 op_sel_hi:[1,0]
	v_pk_mul_f32 v[44:45], v[44:45], v[76:77] op_sel_hi:[1,0]
	s_waitcnt lgkmcnt(0)
	v_pk_fma_f32 v[94:95], v[86:87], v[46:47], v[94:95]
	v_pk_mul_f32 v[46:47], v[48:49], v[76:77] op_sel_hi:[1,0]
	v_pk_add_f32 v[48:49], v[92:93], 1.0 op_sel_hi:[1,0]
	v_pk_mul_f32 v[46:47], v[88:89], v[46:47]
	ds_read_b128 v[86:89], v100
	v_pk_fma_f32 v[92:93], v[48:49], v[46:47], v[96:97]
	v_cvt_pk_bf16_f32 v48, v94, v95
	v_cvt_pk_bf16_f32 v49, v92, v93
	v_lshl_add_u64 v[46:47], v[66:67], 0, s[2:3]
	global_store_dwordx2 v[46:47], v[48:49], off
	s_waitcnt lgkmcnt(0)
	v_mul_f32_e32 v48, v87, v95
	v_fmac_f32_e32 v48, v86, v94
	v_fmac_f32_e32 v48, v88, v92
	v_fmac_f32_e32 v48, v89, v93
	ds_read_b128 v[86:89], v100 offset:4096
	v_add_f32_e32 v103, 0, v48
	v_pk_mul_f32 v[38:39], v[38:39], v[76:77] op_sel_hi:[1,0]
	v_pk_mul_f32 v[34:35], v[34:35], v[76:77] op_sel_hi:[1,0]
	v_pk_mul_f32 v[36:37], v[36:37], v[76:77] op_sel_hi:[1,0]
	s_waitcnt lgkmcnt(0)
	v_mul_f32_e32 v48, v87, v95
	v_fmac_f32_e32 v48, v86, v94
	v_fmac_f32_e32 v48, v88, v92
	v_fmac_f32_e32 v48, v89, v93
	ds_read_b128 v[86:89], v100 offset:8192
	v_add_f32_e32 v104, 0, v48
	s_waitcnt lgkmcnt(0)
	v_mul_f32_e32 v48, v87, v95
	v_fmac_f32_e32 v48, v86, v94
	v_fmac_f32_e32 v48, v88, v92
	v_fmac_f32_e32 v48, v89, v93
	ds_read_b128 v[86:89], v100 offset:12288
	v_add_f32_e32 v105, 0, v48
	s_waitcnt lgkmcnt(0)
	v_mul_f32_e32 v48, v87, v95
	v_fmac_f32_e32 v48, v86, v94
	v_fmac_f32_e32 v48, v88, v92
	v_fmac_f32_e32 v48, v89, v93
	ds_read_b128 v[88:91], v100 offset:16384
	v_add_f32_e32 v87, 0, v48
	s_waitcnt lgkmcnt(0)
	v_mul_f32_e32 v48, v89, v95
	v_fmac_f32_e32 v48, v88, v94
	v_fmac_f32_e32 v48, v90, v92
	v_fmac_f32_e32 v48, v91, v93
	ds_read_b128 v[88:91], v100 offset:20480
	v_add_f32_e32 v86, 0, v48
	s_waitcnt lgkmcnt(0)
	v_mul_f32_e32 v48, v89, v95
	v_fmac_f32_e32 v48, v88, v94
	v_fmac_f32_e32 v48, v90, v92
	v_fmac_f32_e32 v48, v91, v93
	ds_read_b128 v[88:91], v100 offset:24576
	v_add_f32_e32 v85, 0, v48
	s_waitcnt lgkmcnt(0)
	v_mul_f32_e32 v48, v89, v95
	v_fmac_f32_e32 v48, v88, v94
	v_fmac_f32_e32 v48, v90, v92
	v_fmac_f32_e32 v48, v91, v93
	ds_read_b128 v[88:91], v100 offset:28672
	v_add_f32_e32 v49, 0, v48
	s_waitcnt lgkmcnt(0)
	v_mul_f32_e32 v48, v95, v89
	v_fmac_f32_e32 v48, v94, v88
	v_fmac_f32_e32 v48, v92, v90
	v_fmac_f32_e32 v48, v93, v91
	ds_read_b128 v[88:91], v100 offset:37888
	ds_read_b128 v[92:95], v84 offset:1024
	ds_read_b128 v[96:99], v83 offset:1024
	v_add_f32_e32 v48, 0, v48
	s_waitcnt lgkmcnt(2)
	v_pk_mul_f32 v[42:43], v[42:43], v[88:89]
	s_waitcnt lgkmcnt(1)
	v_pk_add_f32 v[88:89], v[92:93], 1.0 op_sel_hi:[1,0]
	v_pk_mul_f32 v[44:45], v[44:45], v[90:91]
	s_waitcnt lgkmcnt(0)
	v_pk_fma_f32 v[42:43], v[42:43], v[88:89], v[96:97]
	v_pk_add_f32 v[88:89], v[94:95], 1.0 op_sel_hi:[1,0]
	s_nop 0
	v_pk_fma_f32 v[44:45], v[44:45], v[88:89], v[98:99]
	v_cvt_pk_bf16_f32 v88, v42, v43
	v_cvt_pk_bf16_f32 v89, v44, v45
	global_store_dwordx2 v[46:47], v[88:89], off offset:512
	ds_read_b128 v[88:91], v100 offset:1024
	s_waitcnt lgkmcnt(0)
	v_mul_f32_e32 v89, v43, v89
	v_fmac_f32_e32 v89, v42, v88
	v_fmac_f32_e32 v89, v44, v90
	v_fmac_f32_e32 v89, v45, v91
	ds_read_b128 v[90:93], v100 offset:5120
	v_add_f32_e32 v88, v103, v89
	s_waitcnt lgkmcnt(0)
	v_mul_f32_e32 v89, v43, v91
	v_fmac_f32_e32 v89, v42, v90
	v_fmac_f32_e32 v89, v44, v92
	v_fmac_f32_e32 v89, v45, v93
	ds_read_b128 v[90:93], v100 offset:9216
	v_add_f32_e32 v89, v104, v89
	s_waitcnt lgkmcnt(0)
	v_mul_f32_e32 v91, v43, v91
	v_fmac_f32_e32 v91, v42, v90
	v_fmac_f32_e32 v91, v44, v92
	v_fmac_f32_e32 v91, v45, v93
	v_add_f32_e32 v98, v105, v91
	ds_read_b128 v[172:175], v100 offset:13312
	ds_read_b128 v[176:179], v100 offset:17408
	ds_read_b128 v[180:183], v100 offset:21504
	ds_read_b128 v[184:187], v100 offset:25600
	ds_read_b128 v[188:191], v100 offset:29696
	s_waitcnt lgkmcnt(4)
	v_mul_f32_e32 v173, v43, v173
	v_fmac_f32_e32 v173, v42, v172
	v_fmac_f32_e32 v173, v44, v174
	v_fmac_f32_e32 v173, v45, v175
	v_add_f32_e32 v87, v87, v173
	s_waitcnt lgkmcnt(3)
	v_mul_f32_e32 v177, v43, v177
	v_fmac_f32_e32 v177, v42, v176
	v_fmac_f32_e32 v177, v44, v178
	v_fmac_f32_e32 v177, v45, v179
	v_add_f32_e32 v86, v86, v177
	s_waitcnt lgkmcnt(2)
	v_mul_f32_e32 v181, v43, v181
	v_fmac_f32_e32 v181, v42, v180
	v_fmac_f32_e32 v181, v44, v182
	v_fmac_f32_e32 v181, v45, v183
	v_add_f32_e32 v85, v85, v181
	s_waitcnt lgkmcnt(1)
	v_mul_f32_e32 v185, v43, v185
	v_fmac_f32_e32 v185, v42, v184
	v_fmac_f32_e32 v185, v44, v186
	v_fmac_f32_e32 v185, v45, v187
	v_add_f32_e32 v99, v49, v185
	s_waitcnt lgkmcnt(0)
	v_mul_f32_e32 v43, v43, v189
	v_fmac_f32_e32 v43, v42, v188
	v_fmac_f32_e32 v43, v44, v190
	v_fmac_f32_e32 v43, v45, v191
	v_add_f32_e32 v103, v48, v43
	ds_read_b128 v[42:45], v100 offset:38912
	ds_read_b128 v[90:93], v84 offset:2048
	ds_read_b128 v[94:97], v83 offset:2048
	s_waitcnt lgkmcnt(2)
	v_pk_mul_f32 v[38:39], v[38:39], v[42:43]
	s_waitcnt lgkmcnt(1)
	v_pk_add_f32 v[42:43], v[90:91], 1.0 op_sel_hi:[1,0]
	s_waitcnt lgkmcnt(0)
	v_pk_fma_f32 v[48:49], v[38:39], v[42:43], v[94:95]
	v_pk_mul_f32 v[38:39], v[40:41], v[76:77] op_sel_hi:[1,0]
	v_pk_add_f32 v[40:41], v[92:93], 1.0 op_sel_hi:[1,0]
	v_pk_mul_f32 v[38:39], v[38:39], v[44:45]
	s_nop 0
	v_pk_fma_f32 v[44:45], v[38:39], v[40:41], v[96:97]
	v_cvt_pk_bf16_f32 v38, v48, v49
	v_cvt_pk_bf16_f32 v39, v44, v45
	global_store_dwordx2 v[46:47], v[38:39], off offset:1024
	ds_read_b128 v[172:175], v100 offset:2048
	ds_read_b128 v[176:179], v100 offset:6144
	ds_read_b128 v[180:183], v100 offset:10240
	ds_read_b128 v[184:187], v100 offset:14336
	ds_read_b128 v[188:191], v100 offset:18432
	s_waitcnt lgkmcnt(4)
	v_mul_f32_e32 v173, v49, v173
	v_fmac_f32_e32 v173, v48, v172
	v_fmac_f32_e32 v173, v44, v174
	v_fmac_f32_e32 v173, v45, v175
	v_add_f32_e32 v43, v88, v173
	s_waitcnt lgkmcnt(3)
	v_mul_f32_e32 v177, v49, v177
	v_fmac_f32_e32 v177, v48, v176
	v_fmac_f32_e32 v177, v44, v178
	v_fmac_f32_e32 v177, v45, v179
	v_add_f32_e32 v104, v89, v177
	s_waitcnt lgkmcnt(2)
	v_mul_f32_e32 v181, v49, v181
	v_fmac_f32_e32 v181, v48, v180
	v_fmac_f32_e32 v181, v44, v182
	v_fmac_f32_e32 v181, v45, v183
	v_add_f32_e32 v98, v98, v181
	s_waitcnt lgkmcnt(1)
	v_mul_f32_e32 v185, v49, v185
	v_fmac_f32_e32 v185, v48, v184
	v_fmac_f32_e32 v185, v44, v186
	v_fmac_f32_e32 v185, v45, v187
	v_add_f32_e32 v42, v87, v185
	s_waitcnt lgkmcnt(0)
	v_mul_f32_e32 v189, v49, v189
	v_fmac_f32_e32 v189, v48, v188
	v_fmac_f32_e32 v189, v44, v190
	v_fmac_f32_e32 v189, v45, v191
	v_add_f32_e32 v41, v86, v189
	ds_read_b128 v[86:89], v100 offset:22528
	s_waitcnt lgkmcnt(0)
	v_mul_f32_e32 v38, v49, v87
	v_fmac_f32_e32 v38, v48, v86
	v_fmac_f32_e32 v38, v44, v88
	v_fmac_f32_e32 v38, v45, v89
	ds_read_b128 v[86:89], v100 offset:26624
	v_add_f32_e32 v40, v85, v38
	s_waitcnt lgkmcnt(0)
	v_mul_f32_e32 v38, v49, v87
	v_fmac_f32_e32 v38, v48, v86
	v_fmac_f32_e32 v38, v44, v88
	v_fmac_f32_e32 v38, v45, v89
	ds_read_b128 v[86:89], v100 offset:30720
	v_add_f32_e32 v39, v99, v38
	s_waitcnt lgkmcnt(0)
	v_mul_f32_e32 v38, v49, v87
	v_fmac_f32_e32 v38, v48, v86
	v_fmac_f32_e32 v38, v44, v88
	v_fmac_f32_e32 v38, v45, v89
	ds_read_b128 v[86:89], v100 offset:39936
	ds_read_b128 v[90:93], v84 offset:3072
	ds_read_b128 v[94:97], v83 offset:3072
	v_add_f32_e32 v38, v103, v38
	s_waitcnt lgkmcnt(2)
	v_pk_mul_f32 v[34:35], v[34:35], v[86:87]
	s_waitcnt lgkmcnt(1)
	v_pk_add_f32 v[44:45], v[90:91], 1.0 op_sel_hi:[1,0]
	v_pk_mul_f32 v[36:37], v[36:37], v[88:89]
	s_waitcnt lgkmcnt(0)
	v_pk_fma_f32 v[34:35], v[34:35], v[44:45], v[94:95]
	v_pk_add_f32 v[44:45], v[92:93], 1.0 op_sel_hi:[1,0]
	s_nop 0
	v_pk_fma_f32 v[36:37], v[36:37], v[44:45], v[96:97]
	v_cvt_pk_bf16_f32 v44, v34, v35
	v_cvt_pk_bf16_f32 v45, v36, v37
	global_store_dwordx2 v[46:47], v[44:45], off offset:1536
	ds_read_b128 v[172:175], v100 offset:3072
	ds_read_b128 v[176:179], v100 offset:7168
	ds_read_b128 v[180:183], v100 offset:11264
	ds_read_b128 v[184:187], v100 offset:15360
	ds_read_b128 v[188:191], v100 offset:19456
	ds_read_b128 v[204:207], v100 offset:23552
	ds_read_b128 v[208:211], v100 offset:27648
	s_waitcnt lgkmcnt(6)
	v_mul_f32_e32 v173, v35, v173
	v_fmac_f32_e32 v173, v34, v172
	v_fmac_f32_e32 v173, v36, v174
	v_fmac_f32_e32 v173, v37, v175
	v_add_f32_e32 v43, v43, v173
	s_waitcnt lgkmcnt(5)
	v_mul_f32_e32 v177, v35, v177
	v_fmac_f32_e32 v177, v34, v176
	v_fmac_f32_e32 v177, v36, v178
	v_fmac_f32_e32 v177, v37, v179
	v_add_f32_e32 v48, v104, v177
	s_waitcnt lgkmcnt(4)
	v_mul_f32_e32 v181, v35, v181
	v_fmac_f32_e32 v181, v34, v180
	v_fmac_f32_e32 v181, v36, v182
	v_fmac_f32_e32 v181, v37, v183
	v_add_f32_e32 v49, v98, v181
	s_waitcnt lgkmcnt(3)
	v_mul_f32_e32 v185, v35, v185
	v_fmac_f32_e32 v185, v34, v184
	v_fmac_f32_e32 v185, v36, v186
	v_fmac_f32_e32 v185, v37, v187
	v_add_f32_e32 v42, v42, v185
	s_waitcnt lgkmcnt(2)
	v_mul_f32_e32 v189, v35, v189
	v_fmac_f32_e32 v189, v34, v188
	v_fmac_f32_e32 v189, v36, v190
	v_fmac_f32_e32 v189, v37, v191
	v_add_f32_e32 v41, v41, v189
	s_waitcnt lgkmcnt(1)
	v_mul_f32_e32 v205, v35, v205
	v_fmac_f32_e32 v205, v34, v204
	v_fmac_f32_e32 v205, v36, v206
	v_fmac_f32_e32 v205, v37, v207
	v_add_f32_e32 v40, v40, v205
	s_waitcnt lgkmcnt(0)
	v_mul_f32_e32 v209, v35, v209
	v_fmac_f32_e32 v209, v34, v208
	v_fmac_f32_e32 v209, v36, v210
	v_fmac_f32_e32 v209, v37, v211
	v_add_f32_e32 v39, v39, v209
	ds_read_b128 v[44:47], v100 offset:31744
	s_waitcnt lgkmcnt(0)
	v_mul_f32_e32 v35, v35, v45
	v_fmac_f32_e32 v35, v34, v44
	v_fmac_f32_e32 v35, v36, v46
	v_cndmask_b32_e64 v36, v43, v41, s[40:41]
	v_fmac_f32_e32 v35, v37, v47
	ds_bpermute_b32 v36, v249, v36
	v_cndmask_b32_e64 v37, v48, v40, s[40:41]
	v_add_f32_e32 v34, v38, v35
	ds_bpermute_b32 v37, v249, v37
	v_cndmask_b32_e64 v38, v49, v39, s[40:41]
	ds_bpermute_b32 v38, v249, v38
	v_cndmask_b32_e64 v35, v41, v43, s[40:41]
	s_waitcnt lgkmcnt(2)
	v_add_f32_e32 v35, v35, v36
	v_cndmask_b32_e64 v36, v40, v48, s[40:41]
	s_waitcnt lgkmcnt(1)
	v_add_f32_e32 v36, v36, v37
	v_cndmask_b32_e64 v37, v39, v49, s[40:41]
	s_waitcnt lgkmcnt(0)
	v_add_f32_e32 v37, v37, v38
	v_cndmask_b32_e64 v38, v34, v42, s[40:41]
	v_cndmask_b32_e64 v34, v42, v34, s[40:41]
	ds_bpermute_b32 v34, v249, v34
	s_waitcnt lgkmcnt(0)
	v_add_f32_e32 v34, v38, v34
	v_cndmask_b32_e64 v38, v37, v35, s[42:43]
	v_cndmask_b32_e64 v35, v35, v37, s[42:43]
	v_cndmask_b32_e64 v37, v34, v36, s[42:43]
	v_cndmask_b32_e64 v34, v36, v34, s[42:43]
	ds_bpermute_b32 v35, v248, v35
	ds_bpermute_b32 v34, v248, v34
	s_waitcnt lgkmcnt(1)
	v_add_f32_e32 v35, v38, v35
	s_waitcnt lgkmcnt(0)
	v_add_f32_e32 v34, v37, v34
	v_cndmask_b32_e64 v36, v34, v35, s[44:45]
	v_cndmask_b32_e64 v34, v35, v34, s[44:45]
	ds_bpermute_b32 v34, v247, v34
	s_waitcnt lgkmcnt(0)
	v_add_f32_e32 v34, v36, v34
	ds_bpermute_b32 v35, v246, v34
	s_waitcnt lgkmcnt(0)
	v_add_f32_e32 v34, v34, v35
	ds_bpermute_b32 v35, v245, v34
	s_waitcnt lgkmcnt(0)
	v_add_f32_e32 v34, v34, v35
	ds_bpermute_b32 v35, v244, v34
	s_and_saveexec_b64 s[18:19], s[46:47]
	s_cbranch_execz .LBB0_450
	s_lshl_b64 s[2:3], s[52:53], 5
	s_waitcnt lgkmcnt(0)
	v_add_f32_e32 v36, v34, v35
	v_lshl_add_u64 v[34:35], v[64:65], 0, s[2:3]
	global_store_dword v[34:35], v36, off
	s_branch .LBB0_450
